# previous plus scalar-base LDS-DMA loads in the PG, branch and memory-KV loops (no per-load 64-bit address adds)
# speedup vs baseline: 1.0065x; 1.0014x over previous
; #define PG8_STAGE(bufoff, gbase, voff) do { _Pragma("unroll") for (int _i = 0; _i < 2; ++_i) \
;         __builtin_amdgcn_global_load_lds((const unsigned*)((const char*)(gbase) + (voff)[_i]), (LAS unsigned*)(lds + (bufoff) + ldsw + _i * 8192), 16, 0, 0); } while (0)
; #define PG8_LDA(dst, b, h) do { _Pragma("unroll") for (int m = 0; m < 4; ++m) _Pragma("unroll") for (int k = 0; k < 2; ++k) dst[m][k] = *(const LAS bf16x8*)(lds + PG8_SA(b, h) + aoff + m * 2048 + k * 1024); } while (0)
; #define PG8_LDB(dst, b, h) do { _Pragma("unroll") for (int n = 0; n < 2; ++n) _Pragma("unroll") for (int k = 0; k < 2; ++k) dst[n][k] = *(const LAS bf16x8*)(lds + PG8_SB(b, h) + boff + n * 2048 + k * 1024); } while (0)
; #define PG8_WAIT_V(n) asm volatile("s_waitcnt vmcnt(" #n ")" ::: "memory")
; #define PG8_WAIT_L(n) asm volatile("s_waitcnt lgkmcnt(" #n ")" ::: "memory")
; #define PG8_BAR __builtin_amdgcn_s_barrier()
; #define PG8_SCHED __builtin_amdgcn_sched_barrier(0)
; template <class Epi, class Sched>
; DI void gemm_phase(LAS unsigned char* lds, const Sched& S, const Epi& E) {
;     ...
;     for (int t = 0; t < nt; t += 2) {
;       const bool last = (t == nt - 2);
;       const char* a1 = cA + (size_t)(t + 1) * kstep;
;       const char* a2 = last ? nA : cA + (size_t)(t + 2) * kstep; const char* b2 = last ? nB : cB + (size_t)(t + 2) * kstep;
;       const char* a3 = a2 + kstep; const char* b3 = b2 + kstep;
;       PG8_LDB(B0, 0, 0); PG8_LDB(B1, 0, 1); PG8_SCHED; PG8_LDA(At, 0, 0); PG8_STAGE(PG8_SA(1, 1), a1 + hstep, voffA);
;       PG8_WAIT_V(8); PG8_WAIT_L(0); PG8_BAR; PG8_MMA(0, 0, At, B0); PG8_MMA(0, 1, At, B1); PG8_BAR; PG8_SCHED;
;       PG8_LDA(At, 0, 1); PG8_STAGE(PG8_SB(0, 0), b2, voffB); PG8_STAGE(PG8_SB(0, 1), b2 + hstep, voffB); PG8_STAGE(PG8_SA(0, 0), a2, voffA);
;       PG8_WAIT_V(8); PG8_WAIT_L(0); PG8_BAR; PG8_MMA(1, 0, At, B0); PG8_MMA(1, 1, At, B1); PG8_BAR; PG8_SCHED;
;       PG8_LDB(B0, 1, 0); PG8_LDB(B1, 1, 1); PG8_SCHED; PG8_LDA(At, 1, 0); PG8_STAGE(PG8_SA(0, 1), a2 + hstep, voffA);
;       PG8_WAIT_V(8); PG8_WAIT_L(0); PG8_BAR; PG8_MMA(0, 0, At, B0); PG8_MMA(0, 1, At, B1); PG8_BAR; PG8_SCHED;
;       PG8_LDA(At, 1, 1); PG8_STAGE(PG8_SB(1, 0), b3, voffB); PG8_STAGE(PG8_SB(1, 1), b3 + hstep, voffB); PG8_STAGE(PG8_SA(1, 0), a3, voffA);
;       PG8_WAIT_V(8); PG8_WAIT_L(0); PG8_BAR; PG8_MMA(1, 0, At, B0); PG8_MMA(1, 1, At, B1); PG8_BAR; PG8_SCHED;
;     }
.LBB0_139:
	s_add_u32 s26, s48, 0xfff80080
	s_addc_u32 s27, s49, -1
	s_add_i32 s62, 0, 0x10000
	s_cmp_eq_u32 s61, 28
	s_cselect_b32 s51, s25, s27
	s_cselect_b32 s50, s31, s26
	v_add_u32_e32 v138, s62, v141
	s_cselect_b32 s27, s41, s39
	s_cselect_b32 s26, s40, s37
	s_add_i32 s64, 0, 0x14000
	ds_read_b128 v[144:147], v138
	ds_read_b128 v[148:151], v138 offset:1024
	ds_read_b128 v[152:155], v138 offset:2048
	ds_read_b128 v[156:159], v138 offset:3072
	v_add_u32_e32 v138, s64, v141
	ds_read_b128 v[160:163], v138
	ds_read_b128 v[164:167], v138 offset:1024
	ds_read_b128 v[168:171], v138 offset:2048
	ds_read_b128 v[172:175], v138 offset:3072
	s_add_i32 m0, s45, 0xc000
	ds_read_b128 v[176:179], v143
	ds_read_b128 v[180:183], v143 offset:1024
	ds_read_b128 v[184:187], v143 offset:2048
	ds_read_b128 v[188:191], v143 offset:3072
	ds_read_b128 v[192:195], v143 offset:4096
	ds_read_b128 v[196:199], v143 offset:5120
	ds_read_b128 v[200:203], v143 offset:6144
	ds_read_b128 v[204:207], v143 offset:7168
	global_load_lds_dwordx4 v134, s[48:49]
	s_add_i32 m0, s45, 0xe000
	s_nop 0
	global_load_lds_dwordx4 v136, s[48:49]
	s_waitcnt vmcnt(8) lgkmcnt(0)
	s_setprio 1
	s_barrier
	v_mfma_f32_16x16x32_bf16 v[124:127], v[144:147], v[176:179], v[124:127]
	v_mfma_f32_16x16x32_bf16 v[120:123], v[152:155], v[176:179], v[120:123]
	v_mfma_f32_16x16x32_bf16 v[116:119], v[144:147], v[184:187], v[116:119]
	v_mfma_f32_16x16x32_bf16 v[108:111], v[152:155], v[184:187], v[108:111]
	v_mfma_f32_16x16x32_bf16 v[100:103], v[144:147], v[192:195], v[100:103]
	v_mfma_f32_16x16x32_bf16 v[92:95], v[152:155], v[192:195], v[92:95]
	v_mfma_f32_16x16x32_bf16 v[84:87], v[144:147], v[200:203], v[84:87]
	v_mfma_f32_16x16x32_bf16 v[76:79], v[152:155], v[200:203], v[76:79]
	v_mfma_f32_16x16x32_bf16 v[124:127], v[148:151], v[180:183], v[124:127]
	v_mfma_f32_16x16x32_bf16 v[120:123], v[156:159], v[180:183], v[120:123]
	v_mfma_f32_16x16x32_bf16 v[116:119], v[148:151], v[188:191], v[116:119]
	v_mfma_f32_16x16x32_bf16 v[108:111], v[156:159], v[188:191], v[108:111]
	v_mfma_f32_16x16x32_bf16 v[100:103], v[148:151], v[196:199], v[100:103]
	v_mfma_f32_16x16x32_bf16 v[92:95], v[156:159], v[196:199], v[92:95]
	v_mfma_f32_16x16x32_bf16 v[84:87], v[148:151], v[204:207], v[84:87]
	v_mfma_f32_16x16x32_bf16 v[76:79], v[156:159], v[204:207], v[76:79]
	v_mfma_f32_16x16x32_bf16 v[112:115], v[160:163], v[176:179], v[112:115]
	v_mfma_f32_16x16x32_bf16 v[104:107], v[168:171], v[176:179], v[104:107]
	v_mfma_f32_16x16x32_bf16 v[96:99], v[160:163], v[184:187], v[96:99]
	v_mfma_f32_16x16x32_bf16 v[88:91], v[168:171], v[184:187], v[88:91]
	v_mfma_f32_16x16x32_bf16 v[80:83], v[160:163], v[192:195], v[80:83]
	v_mfma_f32_16x16x32_bf16 v[72:75], v[168:171], v[192:195], v[72:75]
	v_mfma_f32_16x16x32_bf16 v[68:71], v[160:163], v[200:203], v[68:71]
	v_mfma_f32_16x16x32_bf16 v[64:67], v[168:171], v[200:203], v[64:67]
	v_mfma_f32_16x16x32_bf16 v[112:115], v[164:167], v[180:183], v[112:115]
	v_mfma_f32_16x16x32_bf16 v[104:107], v[172:175], v[180:183], v[104:107]
	v_mfma_f32_16x16x32_bf16 v[96:99], v[164:167], v[188:191], v[96:99]
	v_mfma_f32_16x16x32_bf16 v[88:91], v[172:175], v[188:191], v[88:91]
	v_mfma_f32_16x16x32_bf16 v[80:83], v[164:167], v[196:199], v[80:83]
	v_mfma_f32_16x16x32_bf16 v[72:75], v[172:175], v[196:199], v[72:75]
	v_mfma_f32_16x16x32_bf16 v[68:71], v[164:167], v[204:207], v[68:71]
	v_mfma_f32_16x16x32_bf16 v[64:67], v[172:175], v[204:207], v[64:67]
	s_barrier
	s_add_u32 s72, s26, s6
	s_addc_u32 s73, s27, s7
	s_add_u32 s74, s50, s6
	s_addc_u32 s75, s51, s7
	s_setprio 0
	s_add_i32 s62, s62, s52
	s_mov_b32 m0, s62
	ds_read_b128 v[176:179], v143 offset:16384
	ds_read_b128 v[180:183], v143 offset:17408
	ds_read_b128 v[184:187], v143 offset:18432
	ds_read_b128 v[188:191], v143 offset:19456
	ds_read_b128 v[192:195], v143 offset:20480
	ds_read_b128 v[196:199], v143 offset:21504
	ds_read_b128 v[200:203], v143 offset:22528
	ds_read_b128 v[204:207], v143 offset:23552
	global_load_lds_dwordx4 v208, s[26:27]
	s_add_i32 m0, s62, 0x2000
	s_add_u32 s62, s26, 0x80000
	s_addc_u32 s63, s27, 0
	s_add_i32 s64, s64, s52
	global_load_lds_dwordx4 v132, s[26:27]
	s_mov_b32 m0, s64
	s_nop 0
	global_load_lds_dwordx4 v208, s[62:63]
	s_add_i32 m0, s64, 0x2000
	s_nop 0
	global_load_lds_dwordx4 v132, s[62:63]
	s_mov_b32 m0, s45
	s_nop 0
	global_load_lds_dwordx4 v128, s[50:51]
	s_mov_b32 m0, s47
	s_nop 0
	global_load_lds_dwordx4 v130, s[50:51]
	s_waitcnt vmcnt(8) lgkmcnt(0)
	s_setprio 1
	s_barrier
	v_mfma_f32_16x16x32_bf16 v[60:63], v[144:147], v[176:179], v[60:63]
	v_mfma_f32_16x16x32_bf16 v[56:59], v[152:155], v[176:179], v[56:59]
	v_mfma_f32_16x16x32_bf16 v[52:55], v[144:147], v[184:187], v[52:55]
	v_mfma_f32_16x16x32_bf16 v[44:47], v[152:155], v[184:187], v[44:47]
	v_mfma_f32_16x16x32_bf16 v[36:39], v[144:147], v[192:195], v[36:39]
	v_mfma_f32_16x16x32_bf16 v[28:31], v[152:155], v[192:195], v[28:31]
	v_mfma_f32_16x16x32_bf16 v[20:23], v[144:147], v[200:203], v[20:23]
	v_mfma_f32_16x16x32_bf16 v[12:15], v[152:155], v[200:203], v[12:15]
	v_mfma_f32_16x16x32_bf16 v[60:63], v[148:151], v[180:183], v[60:63]
	v_mfma_f32_16x16x32_bf16 v[56:59], v[156:159], v[180:183], v[56:59]
	v_mfma_f32_16x16x32_bf16 v[52:55], v[148:151], v[188:191], v[52:55]
	v_mfma_f32_16x16x32_bf16 v[44:47], v[156:159], v[188:191], v[44:47]
	v_mfma_f32_16x16x32_bf16 v[36:39], v[148:151], v[196:199], v[36:39]
	v_mfma_f32_16x16x32_bf16 v[28:31], v[156:159], v[196:199], v[28:31]
	v_mfma_f32_16x16x32_bf16 v[20:23], v[148:151], v[204:207], v[20:23]
	v_mfma_f32_16x16x32_bf16 v[12:15], v[156:159], v[204:207], v[12:15]
	v_mfma_f32_16x16x32_bf16 v[48:51], v[160:163], v[176:179], v[48:51]
	v_mfma_f32_16x16x32_bf16 v[40:43], v[168:171], v[176:179], v[40:43]
	v_mfma_f32_16x16x32_bf16 v[32:35], v[160:163], v[184:187], v[32:35]
	v_mfma_f32_16x16x32_bf16 v[24:27], v[168:171], v[184:187], v[24:27]
	v_mfma_f32_16x16x32_bf16 v[16:19], v[160:163], v[192:195], v[16:19]
	v_mfma_f32_16x16x32_bf16 v[8:11], v[168:171], v[192:195], v[8:11]
	v_mfma_f32_16x16x32_bf16 v[4:7], v[160:163], v[200:203], v[4:7]
	v_mfma_f32_16x16x32_bf16 v[0:3], v[168:171], v[200:203], v[0:3]
	v_mfma_f32_16x16x32_bf16 v[48:51], v[164:167], v[180:183], v[48:51]
	v_mfma_f32_16x16x32_bf16 v[40:43], v[172:175], v[180:183], v[40:43]
	v_mfma_f32_16x16x32_bf16 v[32:35], v[164:167], v[188:191], v[32:35]
	v_mfma_f32_16x16x32_bf16 v[24:27], v[172:175], v[188:191], v[24:27]
	v_mfma_f32_16x16x32_bf16 v[16:19], v[164:167], v[196:199], v[16:19]
	v_mfma_f32_16x16x32_bf16 v[8:11], v[172:175], v[196:199], v[8:11]
	v_mfma_f32_16x16x32_bf16 v[4:7], v[164:167], v[204:207], v[4:7]
	v_mfma_f32_16x16x32_bf16 v[0:3], v[172:175], v[204:207], v[0:3]
	s_barrier
; #define PG8_STAGE(bufoff, gbase, voff) do { _Pragma("unroll") for (int _i = 0; _i < 2; ++_i) \
;         __builtin_amdgcn_global_load_lds((const unsigned*)((const char*)(gbase) + (voff)[_i]), (LAS unsigned*)(lds + (bufoff) + ldsw + _i * 8192), 16, 0, 0); } while (0)
; #define PG8_LDA(dst, b, h) do { _Pragma("unroll") for (int m = 0; m < 4; ++m) _Pragma("unroll") for (int k = 0; k < 2; ++k) dst[m][k] = *(const LAS bf16x8*)(lds + PG8_SA(b, h) + aoff + m * 2048 + k * 1024); } while (0)
; #define PG8_LDB(dst, b, h) do { _Pragma("unroll") for (int n = 0; n < 2; ++n) _Pragma("unroll") for (int k = 0; k < 2; ++k) dst[n][k] = *(const LAS bf16x8*)(lds + PG8_SB(b, h) + boff + n * 2048 + k * 1024); } while (0)
; #define PG8_WAIT_V(n) asm volatile("s_waitcnt vmcnt(" #n ")" ::: "memory")
; #define PG8_WAIT_L(n) asm volatile("s_waitcnt lgkmcnt(" #n ")" ::: "memory")
; #define PG8_BAR __builtin_amdgcn_s_barrier()
; #define PG8_SCHED __builtin_amdgcn_sched_barrier(0)
; template <class Epi, class Sched>
; DI void gemm_phase(LAS unsigned char* lds, const Sched& S, const Epi& E) {
;     ...
;     for (int t = 0; t < nt; t += 2) {
;       const bool last = (t == nt - 2);
;       const char* a1 = cA + (size_t)(t + 1) * kstep;
;       const char* a2 = last ? nA : cA + (size_t)(t + 2) * kstep; const char* b2 = last ? nB : cB + (size_t)(t + 2) * kstep;
;       const char* a3 = a2 + kstep; const char* b3 = b2 + kstep;
;       PG8_LDB(B0, 0, 0); PG8_LDB(B1, 0, 1); PG8_SCHED; PG8_LDA(At, 0, 0); PG8_STAGE(PG8_SA(1, 1), a1 + hstep, voffA);
;       PG8_WAIT_V(8); PG8_WAIT_L(0); PG8_BAR; PG8_MMA(0, 0, At, B0); PG8_MMA(0, 1, At, B1); PG8_BAR; PG8_SCHED;
;       PG8_LDA(At, 0, 1); PG8_STAGE(PG8_SB(0, 0), b2, voffB); PG8_STAGE(PG8_SB(0, 1), b2 + hstep, voffB); PG8_STAGE(PG8_SA(0, 0), a2, voffA);
;       PG8_WAIT_V(8); PG8_WAIT_L(0); PG8_BAR; PG8_MMA(1, 0, At, B0); PG8_MMA(1, 1, At, B1); PG8_BAR; PG8_SCHED;
;       PG8_LDB(B0, 1, 0); PG8_LDB(B1, 1, 1); PG8_SCHED; PG8_LDA(At, 1, 0); PG8_STAGE(PG8_SA(0, 1), a2 + hstep, voffA);
;       PG8_WAIT_V(8); PG8_WAIT_L(0); PG8_BAR; PG8_MMA(0, 0, At, B0); PG8_MMA(0, 1, At, B1); PG8_BAR; PG8_SCHED;
;       PG8_LDA(At, 1, 1); PG8_STAGE(PG8_SB(1, 0), b3, voffB); PG8_STAGE(PG8_SB(1, 1), b3 + hstep, voffB); PG8_STAGE(PG8_SA(1, 0), a3, voffA);
;       PG8_WAIT_V(8); PG8_WAIT_L(0); PG8_BAR; PG8_MMA(1, 0, At, B0); PG8_MMA(1, 1, At, B1); PG8_BAR; PG8_SCHED;
;     }
	s_setprio 0
	s_add_i32 s62, 0, 0x18000
	s_add_i32 s63, 0, 0x1c000
	v_add_u32_e32 v156, s62, v141
	v_add_u32_e32 v172, s63, v141
	ds_read_b128 v[144:147], v156
	ds_read_b128 v[148:151], v156 offset:1024
	ds_read_b128 v[152:155], v156 offset:2048
	ds_read_b128 v[156:159], v156 offset:3072
	ds_read_b128 v[160:163], v172
	ds_read_b128 v[164:167], v172 offset:1024
	ds_read_b128 v[168:171], v172 offset:2048
	ds_read_b128 v[172:175], v172 offset:3072
	s_add_u32 s50, s50, 0x80000
	s_addc_u32 s51, s51, 0
	s_mov_b32 m0, s55
	ds_read_b128 v[176:179], v143 offset:32768
	ds_read_b128 v[180:183], v143 offset:33792
	ds_read_b128 v[184:187], v143 offset:34816
	ds_read_b128 v[188:191], v143 offset:35840
	ds_read_b128 v[192:195], v143 offset:36864
	ds_read_b128 v[196:199], v143 offset:37888
	ds_read_b128 v[200:203], v143 offset:38912
	ds_read_b128 v[204:207], v143 offset:39936
	global_load_lds_dwordx4 v128, s[50:51]
	s_mov_b32 m0, s56
	s_nop 0
	global_load_lds_dwordx4 v130, s[50:51]
	s_waitcnt vmcnt(8) lgkmcnt(0)
	s_setprio 1
	s_barrier
	v_mfma_f32_16x16x32_bf16 v[124:127], v[144:147], v[176:179], v[124:127]
	v_mfma_f32_16x16x32_bf16 v[120:123], v[152:155], v[176:179], v[120:123]
	v_mfma_f32_16x16x32_bf16 v[116:119], v[144:147], v[184:187], v[116:119]
	v_mfma_f32_16x16x32_bf16 v[108:111], v[152:155], v[184:187], v[108:111]
	v_mfma_f32_16x16x32_bf16 v[100:103], v[144:147], v[192:195], v[100:103]
	v_mfma_f32_16x16x32_bf16 v[92:95], v[152:155], v[192:195], v[92:95]
	v_mfma_f32_16x16x32_bf16 v[84:87], v[144:147], v[200:203], v[84:87]
	v_mfma_f32_16x16x32_bf16 v[76:79], v[152:155], v[200:203], v[76:79]
	v_mfma_f32_16x16x32_bf16 v[124:127], v[148:151], v[180:183], v[124:127]
	v_mfma_f32_16x16x32_bf16 v[120:123], v[156:159], v[180:183], v[120:123]
	v_mfma_f32_16x16x32_bf16 v[116:119], v[148:151], v[188:191], v[116:119]
	v_mfma_f32_16x16x32_bf16 v[108:111], v[156:159], v[188:191], v[108:111]
	v_mfma_f32_16x16x32_bf16 v[100:103], v[148:151], v[196:199], v[100:103]
	v_mfma_f32_16x16x32_bf16 v[92:95], v[156:159], v[196:199], v[92:95]
	v_mfma_f32_16x16x32_bf16 v[84:87], v[148:151], v[204:207], v[84:87]
	v_mfma_f32_16x16x32_bf16 v[76:79], v[156:159], v[204:207], v[76:79]
	v_mfma_f32_16x16x32_bf16 v[112:115], v[160:163], v[176:179], v[112:115]
	v_mfma_f32_16x16x32_bf16 v[104:107], v[168:171], v[176:179], v[104:107]
	v_mfma_f32_16x16x32_bf16 v[96:99], v[160:163], v[184:187], v[96:99]
	v_mfma_f32_16x16x32_bf16 v[88:91], v[168:171], v[184:187], v[88:91]
	v_mfma_f32_16x16x32_bf16 v[80:83], v[160:163], v[192:195], v[80:83]
	v_mfma_f32_16x16x32_bf16 v[72:75], v[168:171], v[192:195], v[72:75]
	v_mfma_f32_16x16x32_bf16 v[68:71], v[160:163], v[200:203], v[68:71]
	v_mfma_f32_16x16x32_bf16 v[64:67], v[168:171], v[200:203], v[64:67]
	v_mfma_f32_16x16x32_bf16 v[112:115], v[164:167], v[180:183], v[112:115]
	v_mfma_f32_16x16x32_bf16 v[104:107], v[172:175], v[180:183], v[104:107]
	v_mfma_f32_16x16x32_bf16 v[96:99], v[164:167], v[188:191], v[96:99]
	v_mfma_f32_16x16x32_bf16 v[88:91], v[172:175], v[188:191], v[88:91]
	v_mfma_f32_16x16x32_bf16 v[80:83], v[164:167], v[196:199], v[80:83]
	v_mfma_f32_16x16x32_bf16 v[72:75], v[172:175], v[196:199], v[72:75]
	v_mfma_f32_16x16x32_bf16 v[68:71], v[164:167], v[204:207], v[68:71]
	v_mfma_f32_16x16x32_bf16 v[64:67], v[172:175], v[204:207], v[64:67]
	s_barrier
	s_setprio 0
	s_add_i32 s50, s62, s52
	s_mov_b32 m0, s50
	ds_read_b128 v[176:179], v143 offset:49152
	ds_read_b128 v[180:183], v143 offset:50176
	ds_read_b128 v[184:187], v143 offset:51200
	ds_read_b128 v[188:191], v143 offset:52224
	ds_read_b128 v[192:195], v143 offset:53248
	ds_read_b128 v[196:199], v143 offset:54272
	ds_read_b128 v[200:203], v143 offset:55296
	ds_read_b128 v[204:207], v143 offset:56320
	global_load_lds_dwordx4 v208, s[72:73]
	s_add_i32 m0, s50, 0x2000
	s_add_u32 s26, s26, 0x80080
	s_addc_u32 s27, s27, 0
	s_add_i32 s50, s63, s52
	global_load_lds_dwordx4 v132, s[72:73]
	s_mov_b32 m0, s50
	s_nop 0
	global_load_lds_dwordx4 v208, s[26:27]
	s_add_i32 m0, s50, 0x2000
	s_nop 0
	global_load_lds_dwordx4 v132, s[26:27]
	s_mov_b32 m0, s57
	s_nop 0
	global_load_lds_dwordx4 v128, s[74:75]
	s_mov_b32 m0, s58
	s_nop 0
	global_load_lds_dwordx4 v130, s[74:75]
	s_waitcnt vmcnt(8) lgkmcnt(0)
	s_setprio 1
	s_barrier
	v_mfma_f32_16x16x32_bf16 v[60:63], v[144:147], v[176:179], v[60:63]
	v_mfma_f32_16x16x32_bf16 v[56:59], v[152:155], v[176:179], v[56:59]
	v_mfma_f32_16x16x32_bf16 v[52:55], v[144:147], v[184:187], v[52:55]
	v_mfma_f32_16x16x32_bf16 v[44:47], v[152:155], v[184:187], v[44:47]
	v_mfma_f32_16x16x32_bf16 v[36:39], v[144:147], v[192:195], v[36:39]
	v_mfma_f32_16x16x32_bf16 v[28:31], v[152:155], v[192:195], v[28:31]
	v_mfma_f32_16x16x32_bf16 v[20:23], v[144:147], v[200:203], v[20:23]
	v_mfma_f32_16x16x32_bf16 v[12:15], v[152:155], v[200:203], v[12:15]
	v_mfma_f32_16x16x32_bf16 v[60:63], v[148:151], v[180:183], v[60:63]
	v_mfma_f32_16x16x32_bf16 v[56:59], v[156:159], v[180:183], v[56:59]
	v_mfma_f32_16x16x32_bf16 v[52:55], v[148:151], v[188:191], v[52:55]
	v_mfma_f32_16x16x32_bf16 v[44:47], v[156:159], v[188:191], v[44:47]
	v_mfma_f32_16x16x32_bf16 v[36:39], v[148:151], v[196:199], v[36:39]
	v_mfma_f32_16x16x32_bf16 v[28:31], v[156:159], v[196:199], v[28:31]
	v_mfma_f32_16x16x32_bf16 v[20:23], v[148:151], v[204:207], v[20:23]
	v_mfma_f32_16x16x32_bf16 v[12:15], v[156:159], v[204:207], v[12:15]
	v_mfma_f32_16x16x32_bf16 v[48:51], v[160:163], v[176:179], v[48:51]
	v_mfma_f32_16x16x32_bf16 v[40:43], v[168:171], v[176:179], v[40:43]
	v_mfma_f32_16x16x32_bf16 v[32:35], v[160:163], v[184:187], v[32:35]
	v_mfma_f32_16x16x32_bf16 v[24:27], v[168:171], v[184:187], v[24:27]
	v_mfma_f32_16x16x32_bf16 v[16:19], v[160:163], v[192:195], v[16:19]
	v_mfma_f32_16x16x32_bf16 v[8:11], v[168:171], v[192:195], v[8:11]
	v_mfma_f32_16x16x32_bf16 v[4:7], v[160:163], v[200:203], v[4:7]
	v_mfma_f32_16x16x32_bf16 v[0:3], v[168:171], v[200:203], v[0:3]
	v_mfma_f32_16x16x32_bf16 v[48:51], v[164:167], v[180:183], v[48:51]
	v_mfma_f32_16x16x32_bf16 v[40:43], v[172:175], v[180:183], v[40:43]
	v_mfma_f32_16x16x32_bf16 v[32:35], v[164:167], v[188:191], v[32:35]
	v_mfma_f32_16x16x32_bf16 v[24:27], v[172:175], v[188:191], v[24:27]
	v_mfma_f32_16x16x32_bf16 v[16:19], v[164:167], v[196:199], v[16:19]
	v_mfma_f32_16x16x32_bf16 v[8:11], v[172:175], v[196:199], v[8:11]
	v_mfma_f32_16x16x32_bf16 v[4:7], v[164:167], v[204:207], v[4:7]
	v_mfma_f32_16x16x32_bf16 v[0:3], v[172:175], v[204:207], v[0:3]
	s_barrier
	s_setprio 0
	s_add_i32 s61, s61, 2
	s_add_u32 s48, s48, 0x100
	s_addc_u32 s49, s49, 0
	s_add_u32 s37, s37, 0x100
	s_addc_u32 s39, s39, 0
	s_cmp_gt_u32 s61, 29
	s_cbranch_scc0 .LBB0_139
	s_and_b64 vcc, exec, s[22:23]
	s_cbranch_vccz .LBB0_142
	s_barrier

; #define PG8_STAGE(bufoff, gbase, voff) do { _Pragma("unroll") for (int _i = 0; _i < 2; ++_i) \
;         __builtin_amdgcn_global_load_lds((const unsigned*)((const char*)(gbase) + (voff)[_i]), (LAS unsigned*)(lds + (bufoff) + ldsw + _i * 8192), 16, 0, 0); } while (0)
; #define PG8_LDA(dst, b, h) do { _Pragma("unroll") for (int m = 0; m < 4; ++m) _Pragma("unroll") for (int k = 0; k < 2; ++k) dst[m][k] = *(const LAS bf16x8*)(lds + PG8_SA(b, h) + aoff + m * 2048 + k * 1024); } while (0)
; #define PG8_LDB(dst, b, h) do { _Pragma("unroll") for (int n = 0; n < 2; ++n) _Pragma("unroll") for (int k = 0; k < 2; ++k) dst[n][k] = *(const LAS bf16x8*)(lds + PG8_SB(b, h) + boff + n * 2048 + k * 1024); } while (0)
; #define PG8_WAIT_V(n) asm volatile("s_waitcnt vmcnt(" #n ")" ::: "memory")
; #define PG8_WAIT_L(n) asm volatile("s_waitcnt lgkmcnt(" #n ")" ::: "memory")
; #define PG8_BAR __builtin_amdgcn_s_barrier()
; #define PG8_SCHED __builtin_amdgcn_sched_barrier(0)
; template <class Epi, class Sched>
; DI void gemm_phase(LAS unsigned char* lds, const Sched& S, const Epi& E) {
;     ...
;     for (int t = 0; t < nt; t += 2) {
;       const bool last = (t == nt - 2);
;       const char* a1 = cA + (size_t)(t + 1) * kstep;
;       const char* a2 = last ? nA : cA + (size_t)(t + 2) * kstep; const char* b2 = last ? nB : cB + (size_t)(t + 2) * kstep;
;       const char* a3 = a2 + kstep; const char* b3 = b2 + kstep;
;       PG8_LDB(B0, 0, 0); PG8_LDB(B1, 0, 1); PG8_SCHED; PG8_LDA(At, 0, 0); PG8_STAGE(PG8_SA(1, 1), a1 + hstep, voffA);
;       PG8_WAIT_V(8); PG8_WAIT_L(0); PG8_BAR; PG8_MMA(0, 0, At, B0); PG8_MMA(0, 1, At, B1); PG8_BAR; PG8_SCHED;
;       PG8_LDA(At, 0, 1); PG8_STAGE(PG8_SB(0, 0), b2, voffB); PG8_STAGE(PG8_SB(0, 1), b2 + hstep, voffB); PG8_STAGE(PG8_SA(0, 0), a2, voffA);
;       PG8_WAIT_V(8); PG8_WAIT_L(0); PG8_BAR; PG8_MMA(1, 0, At, B0); PG8_MMA(1, 1, At, B1); PG8_BAR; PG8_SCHED;
;       PG8_LDB(B0, 1, 0); PG8_LDB(B1, 1, 1); PG8_SCHED; PG8_LDA(At, 1, 0); PG8_STAGE(PG8_SA(0, 1), a2 + hstep, voffA);
;       PG8_WAIT_V(8); PG8_WAIT_L(0); PG8_BAR; PG8_MMA(0, 0, At, B0); PG8_MMA(0, 1, At, B1); PG8_BAR; PG8_SCHED;
;       PG8_LDA(At, 1, 1); PG8_STAGE(PG8_SB(1, 0), b3, voffB); PG8_STAGE(PG8_SB(1, 1), b3 + hstep, voffB); PG8_STAGE(PG8_SA(1, 0), a3, voffA);
;       PG8_WAIT_V(8); PG8_WAIT_L(0); PG8_BAR; PG8_MMA(1, 0, At, B0); PG8_MMA(1, 1, At, B1); PG8_BAR; PG8_SCHED;
;     }
.LBB0_790:
	s_add_u32 s22, s24, 0xfffc0080
	s_addc_u32 s23, s25, -1
	s_add_i32 s63, 0, 0x10000
	s_cmp_eq_u32 s62, 12
	s_cselect_b32 s27, s39, s23
	s_cselect_b32 s26, s49, s22
	s_cselect_b32 s23, s43, s61
	s_cselect_b32 s22, s47, s60
	s_add_i32 s66, 0, 0x14000
	v_add_u32_e32 v140, s63, v219
	v_add_u32_e32 v156, s66, v219
	ds_read_b128 v[128:131], v140
	ds_read_b128 v[132:135], v140 offset:1024
	ds_read_b128 v[136:139], v140 offset:2048
	ds_read_b128 v[140:143], v140 offset:3072
	ds_read_b128 v[144:147], v156
	ds_read_b128 v[148:151], v156 offset:1024
	ds_read_b128 v[152:155], v156 offset:2048
	ds_read_b128 v[156:159], v156 offset:3072
	s_add_i32 m0, s44, 0xc000
	ds_read_b128 v[160:163], v221
	ds_read_b128 v[164:167], v221 offset:1024
	ds_read_b128 v[168:171], v221 offset:2048
	ds_read_b128 v[172:175], v221 offset:3072
	ds_read_b128 v[176:179], v221 offset:4096
	ds_read_b128 v[180:183], v221 offset:5120
	ds_read_b128 v[184:187], v221 offset:6144
	ds_read_b128 v[188:191], v221 offset:7168
	global_load_lds_dwordx4 v198, s[24:25]
	s_add_i32 m0, s44, 0xe000
	s_nop 0
	global_load_lds_dwordx4 v200, s[24:25]
	s_waitcnt vmcnt(8) lgkmcnt(0)
	s_setprio 1
	s_barrier
	v_mfma_f32_16x16x32_bf16 v[124:127], v[128:131], v[160:163], v[124:127]
	v_mfma_f32_16x16x32_bf16 v[120:123], v[136:139], v[160:163], v[120:123]
	v_mfma_f32_16x16x32_bf16 v[116:119], v[128:131], v[168:171], v[116:119]
	v_mfma_f32_16x16x32_bf16 v[112:115], v[136:139], v[168:171], v[112:115]
	v_mfma_f32_16x16x32_bf16 v[108:111], v[128:131], v[176:179], v[108:111]
	v_mfma_f32_16x16x32_bf16 v[104:107], v[136:139], v[176:179], v[104:107]
	v_mfma_f32_16x16x32_bf16 v[100:103], v[128:131], v[184:187], v[100:103]
	v_mfma_f32_16x16x32_bf16 v[96:99], v[136:139], v[184:187], v[96:99]
	v_mfma_f32_16x16x32_bf16 v[124:127], v[132:135], v[164:167], v[124:127]
	v_mfma_f32_16x16x32_bf16 v[120:123], v[140:143], v[164:167], v[120:123]
	v_mfma_f32_16x16x32_bf16 v[116:119], v[132:135], v[172:175], v[116:119]
	v_mfma_f32_16x16x32_bf16 v[112:115], v[140:143], v[172:175], v[112:115]
	v_mfma_f32_16x16x32_bf16 v[108:111], v[132:135], v[180:183], v[108:111]
	v_mfma_f32_16x16x32_bf16 v[104:107], v[140:143], v[180:183], v[104:107]
	v_mfma_f32_16x16x32_bf16 v[100:103], v[132:135], v[188:191], v[100:103]
	v_mfma_f32_16x16x32_bf16 v[96:99], v[140:143], v[188:191], v[96:99]
	v_mfma_f32_16x16x32_bf16 v[92:95], v[144:147], v[160:163], v[92:95]
	v_mfma_f32_16x16x32_bf16 v[88:91], v[152:155], v[160:163], v[88:91]
	v_mfma_f32_16x16x32_bf16 v[84:87], v[144:147], v[168:171], v[84:87]
	v_mfma_f32_16x16x32_bf16 v[80:83], v[152:155], v[168:171], v[80:83]
	v_mfma_f32_16x16x32_bf16 v[76:79], v[144:147], v[176:179], v[76:79]
	v_mfma_f32_16x16x32_bf16 v[72:75], v[152:155], v[176:179], v[72:75]
	v_mfma_f32_16x16x32_bf16 v[68:71], v[144:147], v[184:187], v[68:71]
	v_mfma_f32_16x16x32_bf16 v[64:67], v[152:155], v[184:187], v[64:67]
	v_mfma_f32_16x16x32_bf16 v[92:95], v[148:151], v[164:167], v[92:95]
	v_mfma_f32_16x16x32_bf16 v[88:91], v[156:159], v[164:167], v[88:91]
	v_mfma_f32_16x16x32_bf16 v[84:87], v[148:151], v[172:175], v[84:87]
	v_mfma_f32_16x16x32_bf16 v[80:83], v[156:159], v[172:175], v[80:83]
	v_mfma_f32_16x16x32_bf16 v[76:79], v[148:151], v[180:183], v[76:79]
	v_mfma_f32_16x16x32_bf16 v[72:75], v[156:159], v[180:183], v[72:75]
	v_mfma_f32_16x16x32_bf16 v[68:71], v[148:151], v[188:191], v[68:71]
	v_mfma_f32_16x16x32_bf16 v[64:67], v[156:159], v[188:191], v[64:67]
	s_barrier
	s_add_u32 s72, s22, s6
	s_addc_u32 s73, s23, s7
	s_add_u32 s74, s26, s6
	s_addc_u32 s75, s27, s7
	s_setprio 0
	s_add_i32 s63, s63, s12
	s_mov_b32 m0, s63
	ds_read_b128 v[160:163], v221 offset:16384
	ds_read_b128 v[164:167], v221 offset:17408
	ds_read_b128 v[168:171], v221 offset:18432
	ds_read_b128 v[172:175], v221 offset:19456
	ds_read_b128 v[176:179], v221 offset:20480
	ds_read_b128 v[180:183], v221 offset:21504
	ds_read_b128 v[184:187], v221 offset:22528
	ds_read_b128 v[188:191], v221 offset:23552
	global_load_lds_dwordx4 v208, s[22:23]
	s_add_i32 m0, s63, 0x2000
	s_add_u32 s64, s22, 0x40000
	s_addc_u32 s65, s23, 0
	s_add_i32 s63, s66, s12
	global_load_lds_dwordx4 v196, s[22:23]
	s_mov_b32 m0, s63
	s_nop 0
	global_load_lds_dwordx4 v208, s[64:65]
	s_add_i32 m0, s63, 0x2000
	s_nop 0
	global_load_lds_dwordx4 v196, s[64:65]
	s_mov_b32 m0, s44
	s_nop 0
	global_load_lds_dwordx4 v192, s[26:27]
	s_mov_b32 m0, s45
	s_nop 0
	global_load_lds_dwordx4 v194, s[26:27]
	s_waitcnt vmcnt(8) lgkmcnt(0)
	s_setprio 1
	s_barrier
	v_mfma_f32_16x16x32_bf16 v[60:63], v[128:131], v[160:163], v[60:63]
	v_mfma_f32_16x16x32_bf16 v[56:59], v[136:139], v[160:163], v[56:59]
	v_mfma_f32_16x16x32_bf16 v[52:55], v[128:131], v[168:171], v[52:55]
	v_mfma_f32_16x16x32_bf16 v[48:51], v[136:139], v[168:171], v[48:51]
	v_mfma_f32_16x16x32_bf16 v[44:47], v[128:131], v[176:179], v[44:47]
	v_mfma_f32_16x16x32_bf16 v[40:43], v[136:139], v[176:179], v[40:43]
	v_mfma_f32_16x16x32_bf16 v[36:39], v[128:131], v[184:187], v[36:39]
	v_mfma_f32_16x16x32_bf16 v[32:35], v[136:139], v[184:187], v[32:35]
	v_mfma_f32_16x16x32_bf16 v[60:63], v[132:135], v[164:167], v[60:63]
	v_mfma_f32_16x16x32_bf16 v[56:59], v[140:143], v[164:167], v[56:59]
	v_mfma_f32_16x16x32_bf16 v[52:55], v[132:135], v[172:175], v[52:55]
	v_mfma_f32_16x16x32_bf16 v[48:51], v[140:143], v[172:175], v[48:51]
	v_mfma_f32_16x16x32_bf16 v[44:47], v[132:135], v[180:183], v[44:47]
	v_mfma_f32_16x16x32_bf16 v[40:43], v[140:143], v[180:183], v[40:43]
	v_mfma_f32_16x16x32_bf16 v[36:39], v[132:135], v[188:191], v[36:39]
	v_mfma_f32_16x16x32_bf16 v[32:35], v[140:143], v[188:191], v[32:35]
	v_mfma_f32_16x16x32_bf16 v[28:31], v[144:147], v[160:163], v[28:31]
	v_mfma_f32_16x16x32_bf16 v[24:27], v[152:155], v[160:163], v[24:27]
	v_mfma_f32_16x16x32_bf16 v[20:23], v[144:147], v[168:171], v[20:23]
	v_mfma_f32_16x16x32_bf16 v[16:19], v[152:155], v[168:171], v[16:19]
	v_mfma_f32_16x16x32_bf16 v[12:15], v[144:147], v[176:179], v[12:15]
	v_mfma_f32_16x16x32_bf16 v[8:11], v[152:155], v[176:179], v[8:11]
	v_mfma_f32_16x16x32_bf16 v[4:7], v[144:147], v[184:187], v[4:7]
	v_mfma_f32_16x16x32_bf16 v[0:3], v[152:155], v[184:187], v[0:3]
	v_mfma_f32_16x16x32_bf16 v[28:31], v[148:151], v[164:167], v[28:31]
	v_mfma_f32_16x16x32_bf16 v[24:27], v[156:159], v[164:167], v[24:27]
	v_mfma_f32_16x16x32_bf16 v[20:23], v[148:151], v[172:175], v[20:23]
	v_mfma_f32_16x16x32_bf16 v[16:19], v[156:159], v[172:175], v[16:19]
	v_mfma_f32_16x16x32_bf16 v[12:15], v[148:151], v[180:183], v[12:15]
	v_mfma_f32_16x16x32_bf16 v[8:11], v[156:159], v[180:183], v[8:11]
	v_mfma_f32_16x16x32_bf16 v[4:7], v[148:151], v[188:191], v[4:7]
	v_mfma_f32_16x16x32_bf16 v[0:3], v[156:159], v[188:191], v[0:3]
	s_barrier
; #define PG8_STAGE(bufoff, gbase, voff) do { _Pragma("unroll") for (int _i = 0; _i < 2; ++_i) \
;         __builtin_amdgcn_global_load_lds((const unsigned*)((const char*)(gbase) + (voff)[_i]), (LAS unsigned*)(lds + (bufoff) + ldsw + _i * 8192), 16, 0, 0); } while (0)
; #define PG8_LDA(dst, b, h) do { _Pragma("unroll") for (int m = 0; m < 4; ++m) _Pragma("unroll") for (int k = 0; k < 2; ++k) dst[m][k] = *(const LAS bf16x8*)(lds + PG8_SA(b, h) + aoff + m * 2048 + k * 1024); } while (0)
; #define PG8_LDB(dst, b, h) do { _Pragma("unroll") for (int n = 0; n < 2; ++n) _Pragma("unroll") for (int k = 0; k < 2; ++k) dst[n][k] = *(const LAS bf16x8*)(lds + PG8_SB(b, h) + boff + n * 2048 + k * 1024); } while (0)
; #define PG8_WAIT_V(n) asm volatile("s_waitcnt vmcnt(" #n ")" ::: "memory")
; #define PG8_WAIT_L(n) asm volatile("s_waitcnt lgkmcnt(" #n ")" ::: "memory")
; #define PG8_BAR __builtin_amdgcn_s_barrier()
; #define PG8_SCHED __builtin_amdgcn_sched_barrier(0)
; template <class Epi, class Sched>
; DI void gemm_phase(LAS unsigned char* lds, const Sched& S, const Epi& E) {
;     ...
;     for (int t = 0; t < nt; t += 2) {
;       const bool last = (t == nt - 2);
;       const char* a1 = cA + (size_t)(t + 1) * kstep;
;       const char* a2 = last ? nA : cA + (size_t)(t + 2) * kstep; const char* b2 = last ? nB : cB + (size_t)(t + 2) * kstep;
;       const char* a3 = a2 + kstep; const char* b3 = b2 + kstep;
;       PG8_LDB(B0, 0, 0); PG8_LDB(B1, 0, 1); PG8_SCHED; PG8_LDA(At, 0, 0); PG8_STAGE(PG8_SA(1, 1), a1 + hstep, voffA);
;       PG8_WAIT_V(8); PG8_WAIT_L(0); PG8_BAR; PG8_MMA(0, 0, At, B0); PG8_MMA(0, 1, At, B1); PG8_BAR; PG8_SCHED;
;       PG8_LDA(At, 0, 1); PG8_STAGE(PG8_SB(0, 0), b2, voffB); PG8_STAGE(PG8_SB(0, 1), b2 + hstep, voffB); PG8_STAGE(PG8_SA(0, 0), a2, voffA);
;       PG8_WAIT_V(8); PG8_WAIT_L(0); PG8_BAR; PG8_MMA(1, 0, At, B0); PG8_MMA(1, 1, At, B1); PG8_BAR; PG8_SCHED;
;       PG8_LDB(B0, 1, 0); PG8_LDB(B1, 1, 1); PG8_SCHED; PG8_LDA(At, 1, 0); PG8_STAGE(PG8_SA(0, 1), a2 + hstep, voffA);
;       PG8_WAIT_V(8); PG8_WAIT_L(0); PG8_BAR; PG8_MMA(0, 0, At, B0); PG8_MMA(0, 1, At, B1); PG8_BAR; PG8_SCHED;
;       PG8_LDA(At, 1, 1); PG8_STAGE(PG8_SB(1, 0), b3, voffB); PG8_STAGE(PG8_SB(1, 1), b3 + hstep, voffB); PG8_STAGE(PG8_SA(1, 0), a3, voffA);
;       PG8_WAIT_V(8); PG8_WAIT_L(0); PG8_BAR; PG8_MMA(1, 0, At, B0); PG8_MMA(1, 1, At, B1); PG8_BAR; PG8_SCHED;
;     }
	s_setprio 0
	s_add_i32 s63, 0, 0x18000
	s_add_i32 s64, 0, 0x1c000
	v_add_u32_e32 v140, s63, v219
	v_add_u32_e32 v156, s64, v219
	ds_read_b128 v[128:131], v140
	ds_read_b128 v[132:135], v140 offset:1024
	ds_read_b128 v[136:139], v140 offset:2048
	ds_read_b128 v[140:143], v140 offset:3072
	ds_read_b128 v[144:147], v156
	ds_read_b128 v[148:151], v156 offset:1024
	ds_read_b128 v[152:155], v156 offset:2048
	ds_read_b128 v[156:159], v156 offset:3072
	s_add_u32 s26, s26, 0x40000
	s_addc_u32 s27, s27, 0
	s_mov_b32 m0, s54
	ds_read_b128 v[160:163], v221 offset:32768
	ds_read_b128 v[164:167], v221 offset:33792
	ds_read_b128 v[168:171], v221 offset:34816
	ds_read_b128 v[172:175], v221 offset:35840
	ds_read_b128 v[176:179], v221 offset:36864
	ds_read_b128 v[180:183], v221 offset:37888
	ds_read_b128 v[184:187], v221 offset:38912
	ds_read_b128 v[188:191], v221 offset:39936
	global_load_lds_dwordx4 v192, s[26:27]
	s_mov_b32 m0, s55
	s_nop 0
	global_load_lds_dwordx4 v194, s[26:27]
	s_waitcnt vmcnt(8) lgkmcnt(0)
	s_setprio 1
	s_barrier
	v_mfma_f32_16x16x32_bf16 v[124:127], v[128:131], v[160:163], v[124:127]
	v_mfma_f32_16x16x32_bf16 v[120:123], v[136:139], v[160:163], v[120:123]
	v_mfma_f32_16x16x32_bf16 v[116:119], v[128:131], v[168:171], v[116:119]
	v_mfma_f32_16x16x32_bf16 v[112:115], v[136:139], v[168:171], v[112:115]
	v_mfma_f32_16x16x32_bf16 v[108:111], v[128:131], v[176:179], v[108:111]
	v_mfma_f32_16x16x32_bf16 v[104:107], v[136:139], v[176:179], v[104:107]
	v_mfma_f32_16x16x32_bf16 v[100:103], v[128:131], v[184:187], v[100:103]
	v_mfma_f32_16x16x32_bf16 v[96:99], v[136:139], v[184:187], v[96:99]
	v_mfma_f32_16x16x32_bf16 v[124:127], v[132:135], v[164:167], v[124:127]
	v_mfma_f32_16x16x32_bf16 v[120:123], v[140:143], v[164:167], v[120:123]
	v_mfma_f32_16x16x32_bf16 v[116:119], v[132:135], v[172:175], v[116:119]
	v_mfma_f32_16x16x32_bf16 v[112:115], v[140:143], v[172:175], v[112:115]
	v_mfma_f32_16x16x32_bf16 v[108:111], v[132:135], v[180:183], v[108:111]
	v_mfma_f32_16x16x32_bf16 v[104:107], v[140:143], v[180:183], v[104:107]
	v_mfma_f32_16x16x32_bf16 v[100:103], v[132:135], v[188:191], v[100:103]
	v_mfma_f32_16x16x32_bf16 v[96:99], v[140:143], v[188:191], v[96:99]
	v_mfma_f32_16x16x32_bf16 v[92:95], v[144:147], v[160:163], v[92:95]
	v_mfma_f32_16x16x32_bf16 v[88:91], v[152:155], v[160:163], v[88:91]
	v_mfma_f32_16x16x32_bf16 v[84:87], v[144:147], v[168:171], v[84:87]
	v_mfma_f32_16x16x32_bf16 v[80:83], v[152:155], v[168:171], v[80:83]
	v_mfma_f32_16x16x32_bf16 v[76:79], v[144:147], v[176:179], v[76:79]
	v_mfma_f32_16x16x32_bf16 v[72:75], v[152:155], v[176:179], v[72:75]
	v_mfma_f32_16x16x32_bf16 v[68:71], v[144:147], v[184:187], v[68:71]
	v_mfma_f32_16x16x32_bf16 v[64:67], v[152:155], v[184:187], v[64:67]
	v_mfma_f32_16x16x32_bf16 v[92:95], v[148:151], v[164:167], v[92:95]
	v_mfma_f32_16x16x32_bf16 v[88:91], v[156:159], v[164:167], v[88:91]
	v_mfma_f32_16x16x32_bf16 v[84:87], v[148:151], v[172:175], v[84:87]
	v_mfma_f32_16x16x32_bf16 v[80:83], v[156:159], v[172:175], v[80:83]
	v_mfma_f32_16x16x32_bf16 v[76:79], v[148:151], v[180:183], v[76:79]
	v_mfma_f32_16x16x32_bf16 v[72:75], v[156:159], v[180:183], v[72:75]
	v_mfma_f32_16x16x32_bf16 v[68:71], v[148:151], v[188:191], v[68:71]
	v_mfma_f32_16x16x32_bf16 v[64:67], v[156:159], v[188:191], v[64:67]
	s_barrier
	s_setprio 0
	s_add_i32 s26, s63, s12
	s_mov_b32 m0, s26
	ds_read_b128 v[160:163], v221 offset:49152
	ds_read_b128 v[164:167], v221 offset:50176
	ds_read_b128 v[168:171], v221 offset:51200
	ds_read_b128 v[172:175], v221 offset:52224
	ds_read_b128 v[176:179], v221 offset:53248
	ds_read_b128 v[180:183], v221 offset:54272
	ds_read_b128 v[184:187], v221 offset:55296
	ds_read_b128 v[188:191], v221 offset:56320
	global_load_lds_dwordx4 v208, s[72:73]
	s_add_i32 m0, s26, 0x2000
	s_add_u32 s22, s22, 0x40080
	s_addc_u32 s23, s23, 0
	s_add_i32 s26, s64, s12
	global_load_lds_dwordx4 v196, s[72:73]
	s_mov_b32 m0, s26
	s_nop 0
	global_load_lds_dwordx4 v208, s[22:23]
	s_add_i32 m0, s26, 0x2000
	s_nop 0
	global_load_lds_dwordx4 v196, s[22:23]
	s_mov_b32 m0, s57
	s_nop 0
	global_load_lds_dwordx4 v192, s[74:75]
	s_mov_b32 m0, s58
	s_nop 0
	global_load_lds_dwordx4 v194, s[74:75]
	s_waitcnt vmcnt(8) lgkmcnt(0)
	s_setprio 1
	s_barrier
	v_mfma_f32_16x16x32_bf16 v[60:63], v[128:131], v[160:163], v[60:63]
	v_mfma_f32_16x16x32_bf16 v[56:59], v[136:139], v[160:163], v[56:59]
	v_mfma_f32_16x16x32_bf16 v[52:55], v[128:131], v[168:171], v[52:55]
	v_mfma_f32_16x16x32_bf16 v[48:51], v[136:139], v[168:171], v[48:51]
	v_mfma_f32_16x16x32_bf16 v[44:47], v[128:131], v[176:179], v[44:47]
	v_mfma_f32_16x16x32_bf16 v[40:43], v[136:139], v[176:179], v[40:43]
	v_mfma_f32_16x16x32_bf16 v[36:39], v[128:131], v[184:187], v[36:39]
	v_mfma_f32_16x16x32_bf16 v[32:35], v[136:139], v[184:187], v[32:35]
	v_mfma_f32_16x16x32_bf16 v[60:63], v[132:135], v[164:167], v[60:63]
	v_mfma_f32_16x16x32_bf16 v[56:59], v[140:143], v[164:167], v[56:59]
	v_mfma_f32_16x16x32_bf16 v[52:55], v[132:135], v[172:175], v[52:55]
	v_mfma_f32_16x16x32_bf16 v[48:51], v[140:143], v[172:175], v[48:51]
	v_mfma_f32_16x16x32_bf16 v[44:47], v[132:135], v[180:183], v[44:47]
	v_mfma_f32_16x16x32_bf16 v[40:43], v[140:143], v[180:183], v[40:43]
	v_mfma_f32_16x16x32_bf16 v[36:39], v[132:135], v[188:191], v[36:39]
	v_mfma_f32_16x16x32_bf16 v[32:35], v[140:143], v[188:191], v[32:35]
	v_mfma_f32_16x16x32_bf16 v[28:31], v[144:147], v[160:163], v[28:31]
	v_mfma_f32_16x16x32_bf16 v[24:27], v[152:155], v[160:163], v[24:27]
	v_mfma_f32_16x16x32_bf16 v[20:23], v[144:147], v[168:171], v[20:23]
	v_mfma_f32_16x16x32_bf16 v[16:19], v[152:155], v[168:171], v[16:19]
	v_mfma_f32_16x16x32_bf16 v[12:15], v[144:147], v[176:179], v[12:15]
	v_mfma_f32_16x16x32_bf16 v[8:11], v[152:155], v[176:179], v[8:11]
	v_mfma_f32_16x16x32_bf16 v[4:7], v[144:147], v[184:187], v[4:7]
	v_mfma_f32_16x16x32_bf16 v[0:3], v[152:155], v[184:187], v[0:3]
	v_mfma_f32_16x16x32_bf16 v[28:31], v[148:151], v[164:167], v[28:31]
	v_mfma_f32_16x16x32_bf16 v[24:27], v[156:159], v[164:167], v[24:27]
	v_mfma_f32_16x16x32_bf16 v[20:23], v[148:151], v[172:175], v[20:23]
	v_mfma_f32_16x16x32_bf16 v[16:19], v[156:159], v[172:175], v[16:19]
	v_mfma_f32_16x16x32_bf16 v[12:15], v[148:151], v[180:183], v[12:15]
	v_mfma_f32_16x16x32_bf16 v[8:11], v[156:159], v[180:183], v[8:11]
	v_mfma_f32_16x16x32_bf16 v[4:7], v[148:151], v[188:191], v[4:7]
	v_mfma_f32_16x16x32_bf16 v[0:3], v[156:159], v[188:191], v[0:3]
	s_barrier
	s_setprio 0
	s_add_i32 s62, s62, 2
	s_add_u32 s24, s24, 0x100
	s_addc_u32 s25, s25, 0
	s_add_u32 s60, s60, 0x100
	s_addc_u32 s61, s61, 0
	s_cmp_gt_u32 s62, 13
	s_cbranch_scc0 .LBB0_790
	s_and_b64 vcc, exec, s[40:41]
	s_cbranch_vccz .LBB0_793
	s_barrier

; #define PG8_STAGE(bufoff, gbase, voff) do { _Pragma("unroll") for (int _i = 0; _i < 2; ++_i) \
;         __builtin_amdgcn_global_load_lds((const unsigned*)((const char*)(gbase) + (voff)[_i]), (LAS unsigned*)(lds + (bufoff) + ldsw + _i * 8192), 16, 0, 0); } while (0)
; #define PG8_LDA(dst, b, h) do { _Pragma("unroll") for (int m = 0; m < 4; ++m) _Pragma("unroll") for (int k = 0; k < 2; ++k) dst[m][k] = *(const LAS bf16x8*)(lds + PG8_SA(b, h) + aoff + m * 2048 + k * 1024); } while (0)
; #define PG8_LDB(dst, b, h) do { _Pragma("unroll") for (int n = 0; n < 2; ++n) _Pragma("unroll") for (int k = 0; k < 2; ++k) dst[n][k] = *(const LAS bf16x8*)(lds + PG8_SB(b, h) + boff + n * 2048 + k * 1024); } while (0)
; #define PG8_WAIT_V(n) asm volatile("s_waitcnt vmcnt(" #n ")" ::: "memory")
; #define PG8_WAIT_L(n) asm volatile("s_waitcnt lgkmcnt(" #n ")" ::: "memory")
; #define PG8_BAR __builtin_amdgcn_s_barrier()
; #define PG8_SCHED __builtin_amdgcn_sched_barrier(0)
; template <class Epi, class Sched>
; DI void gemm_phase(LAS unsigned char* lds, const Sched& S, const Epi& E) {
;     ...
;     for (int t = 0; t < nt; t += 2) {
;       const bool last = (t == nt - 2);
;       const char* a1 = cA + (size_t)(t + 1) * kstep;
;       const char* a2 = last ? nA : cA + (size_t)(t + 2) * kstep; const char* b2 = last ? nB : cB + (size_t)(t + 2) * kstep;
;       const char* a3 = a2 + kstep; const char* b3 = b2 + kstep;
;       PG8_LDB(B0, 0, 0); PG8_LDB(B1, 0, 1); PG8_SCHED; PG8_LDA(At, 0, 0); PG8_STAGE(PG8_SA(1, 1), a1 + hstep, voffA);
;       PG8_WAIT_V(8); PG8_WAIT_L(0); PG8_BAR; PG8_MMA(0, 0, At, B0); PG8_MMA(0, 1, At, B1); PG8_BAR; PG8_SCHED;
;       PG8_LDA(At, 0, 1); PG8_STAGE(PG8_SB(0, 0), b2, voffB); PG8_STAGE(PG8_SB(0, 1), b2 + hstep, voffB); PG8_STAGE(PG8_SA(0, 0), a2, voffA);
;       PG8_WAIT_V(8); PG8_WAIT_L(0); PG8_BAR; PG8_MMA(1, 0, At, B0); PG8_MMA(1, 1, At, B1); PG8_BAR; PG8_SCHED;
;       PG8_LDB(B0, 1, 0); PG8_LDB(B1, 1, 1); PG8_SCHED; PG8_LDA(At, 1, 0); PG8_STAGE(PG8_SA(0, 1), a2 + hstep, voffA);
;       PG8_WAIT_V(8); PG8_WAIT_L(0); PG8_BAR; PG8_MMA(0, 0, At, B0); PG8_MMA(0, 1, At, B1); PG8_BAR; PG8_SCHED;
;       PG8_LDA(At, 1, 1); PG8_STAGE(PG8_SB(1, 0), b3, voffB); PG8_STAGE(PG8_SB(1, 1), b3 + hstep, voffB); PG8_STAGE(PG8_SA(1, 0), a3, voffA);
;       PG8_WAIT_V(8); PG8_WAIT_L(0); PG8_BAR; PG8_MMA(1, 0, At, B0); PG8_MMA(1, 1, At, B1); PG8_BAR; PG8_SCHED;
;     }
.LBB0_969:
	s_add_u32 s26, s36, 0xfff80080
	s_addc_u32 s27, s37, -1
	s_add_i32 s58, 0, 0x10000
	s_cmp_eq_u32 s57, 28
	s_cselect_b32 s49, s25, s27
	s_cselect_b32 s48, s39, s26
	s_cselect_b32 s27, s41, s56
	s_cselect_b32 s26, s43, s55
	s_add_i32 s60, 0, 0x14000
	v_add_u32_e32 v44, s58, v183
	v_add_u32_e32 v166, s60, v183
	ds_read_b128 v[28:31], v44
	ds_read_b128 v[36:39], v44 offset:1024
	ds_read_b128 v[40:43], v44 offset:2048
	ds_read_b128 v[44:47], v44 offset:3072
	ds_read_b128 v[154:157], v166
	ds_read_b128 v[158:161], v166 offset:1024
	ds_read_b128 v[162:165], v166 offset:2048
	ds_read_b128 v[166:169], v166 offset:3072
	s_add_i32 m0, s10, 0xc000
	ds_read_b128 v[170:173], v185
	ds_read_b128 v[174:177], v185 offset:1024
	ds_read_b128 v[178:181], v185 offset:2048
	ds_read_b128 v[186:189], v185 offset:3072
	ds_read_b128 v[190:193], v185 offset:4096
	ds_read_b128 v[194:197], v185 offset:5120
	ds_read_b128 v[198:201], v185 offset:6144
	ds_read_b128 v[202:205], v185 offset:7168
	global_load_lds_dwordx4 v150, s[36:37]
	s_add_i32 m0, s10, 0xe000
	s_nop 0
	global_load_lds_dwordx4 v152, s[36:37]
	s_waitcnt vmcnt(8) lgkmcnt(0)
	s_setprio 1
	s_barrier
	v_mfma_f32_16x16x32_bf16 v[140:143], v[28:31], v[170:173], v[140:143]
	v_mfma_f32_16x16x32_bf16 v[136:139], v[40:43], v[170:173], v[136:139]
	v_mfma_f32_16x16x32_bf16 v[124:127], v[28:31], v[178:181], v[124:127]
	v_mfma_f32_16x16x32_bf16 v[120:123], v[40:43], v[178:181], v[120:123]
	v_mfma_f32_16x16x32_bf16 v[108:111], v[28:31], v[190:193], v[108:111]
	v_mfma_f32_16x16x32_bf16 v[104:107], v[40:43], v[190:193], v[104:107]
	v_mfma_f32_16x16x32_bf16 v[92:95], v[28:31], v[198:201], v[92:95]
	v_mfma_f32_16x16x32_bf16 v[88:91], v[40:43], v[198:201], v[88:91]
	v_mfma_f32_16x16x32_bf16 v[140:143], v[36:39], v[174:177], v[140:143]
	v_mfma_f32_16x16x32_bf16 v[136:139], v[44:47], v[174:177], v[136:139]
	v_mfma_f32_16x16x32_bf16 v[124:127], v[36:39], v[186:189], v[124:127]
	v_mfma_f32_16x16x32_bf16 v[120:123], v[44:47], v[186:189], v[120:123]
	v_mfma_f32_16x16x32_bf16 v[108:111], v[36:39], v[194:197], v[108:111]
	v_mfma_f32_16x16x32_bf16 v[104:107], v[44:47], v[194:197], v[104:107]
	v_mfma_f32_16x16x32_bf16 v[92:95], v[36:39], v[202:205], v[92:95]
	v_mfma_f32_16x16x32_bf16 v[88:91], v[44:47], v[202:205], v[88:91]
	v_mfma_f32_16x16x32_bf16 v[132:135], v[154:157], v[170:173], v[132:135]
	v_mfma_f32_16x16x32_bf16 v[128:131], v[162:165], v[170:173], v[128:131]
	v_mfma_f32_16x16x32_bf16 v[116:119], v[154:157], v[178:181], v[116:119]
	v_mfma_f32_16x16x32_bf16 v[112:115], v[162:165], v[178:181], v[112:115]
	v_mfma_f32_16x16x32_bf16 v[100:103], v[154:157], v[190:193], v[100:103]
	v_mfma_f32_16x16x32_bf16 v[96:99], v[162:165], v[190:193], v[96:99]
	v_mfma_f32_16x16x32_bf16 v[84:87], v[154:157], v[198:201], v[84:87]
	v_mfma_f32_16x16x32_bf16 v[80:83], v[162:165], v[198:201], v[80:83]
	v_mfma_f32_16x16x32_bf16 v[132:135], v[158:161], v[174:177], v[132:135]
	v_mfma_f32_16x16x32_bf16 v[128:131], v[166:169], v[174:177], v[128:131]
	v_mfma_f32_16x16x32_bf16 v[116:119], v[158:161], v[186:189], v[116:119]
	v_mfma_f32_16x16x32_bf16 v[112:115], v[166:169], v[186:189], v[112:115]
	v_mfma_f32_16x16x32_bf16 v[100:103], v[158:161], v[194:197], v[100:103]
	v_mfma_f32_16x16x32_bf16 v[96:99], v[166:169], v[194:197], v[96:99]
	v_mfma_f32_16x16x32_bf16 v[84:87], v[158:161], v[202:205], v[84:87]
	v_mfma_f32_16x16x32_bf16 v[80:83], v[166:169], v[202:205], v[80:83]
	s_barrier
	s_add_u32 s72, s26, s6
	s_addc_u32 s73, s27, s7
	s_add_u32 s74, s48, s6
	s_addc_u32 s75, s49, s7
	s_setprio 0
	s_add_i32 s58, s58, s9
	s_mov_b32 m0, s58
	ds_read_b128 v[170:173], v185 offset:16384
	ds_read_b128 v[174:177], v185 offset:17408
	ds_read_b128 v[178:181], v185 offset:18432
	ds_read_b128 v[186:189], v185 offset:19456
	ds_read_b128 v[190:193], v185 offset:20480
	ds_read_b128 v[194:197], v185 offset:21504
	ds_read_b128 v[198:201], v185 offset:22528
	ds_read_b128 v[202:205], v185 offset:23552
	global_load_lds_dwordx4 v208, s[26:27]
	s_add_i32 m0, s58, 0x2000
	s_add_u32 s58, s26, 0x80000
	s_addc_u32 s59, s27, 0
	s_add_i32 s60, s60, s9
	global_load_lds_dwordx4 v148, s[26:27]
	s_mov_b32 m0, s60
	s_nop 0
	global_load_lds_dwordx4 v208, s[58:59]
	s_add_i32 m0, s60, 0x2000
	s_nop 0
	global_load_lds_dwordx4 v148, s[58:59]
	s_mov_b32 m0, s10
	s_nop 0
	global_load_lds_dwordx4 v144, s[48:49]
	s_mov_b32 m0, s11
	s_nop 0
	global_load_lds_dwordx4 v146, s[48:49]
	s_waitcnt vmcnt(8) lgkmcnt(0)
	s_setprio 1
	s_barrier
	v_mfma_f32_16x16x32_bf16 v[76:79], v[28:31], v[170:173], v[76:79]
	v_mfma_f32_16x16x32_bf16 v[72:75], v[40:43], v[170:173], v[72:75]
	v_mfma_f32_16x16x32_bf16 v[60:63], v[28:31], v[178:181], v[60:63]
	v_mfma_f32_16x16x32_bf16 v[56:59], v[40:43], v[178:181], v[56:59]
	v_mfma_f32_16x16x32_bf16 v[32:35], v[28:31], v[190:193], v[32:35]
	v_mfma_f32_16x16x32_bf16 v[24:27], v[40:43], v[190:193], v[24:27]
	v_mfma_f32_16x16x32_bf16 v[12:15], v[28:31], v[198:201], v[12:15]
	v_mfma_f32_16x16x32_bf16 v[8:11], v[40:43], v[198:201], v[8:11]
	v_mfma_f32_16x16x32_bf16 v[76:79], v[36:39], v[174:177], v[76:79]
	v_mfma_f32_16x16x32_bf16 v[72:75], v[44:47], v[174:177], v[72:75]
	v_mfma_f32_16x16x32_bf16 v[60:63], v[36:39], v[186:189], v[60:63]
	v_mfma_f32_16x16x32_bf16 v[56:59], v[44:47], v[186:189], v[56:59]
	v_mfma_f32_16x16x32_bf16 v[32:35], v[36:39], v[194:197], v[32:35]
	v_mfma_f32_16x16x32_bf16 v[24:27], v[44:47], v[194:197], v[24:27]
	v_mfma_f32_16x16x32_bf16 v[12:15], v[36:39], v[202:205], v[12:15]
	v_mfma_f32_16x16x32_bf16 v[8:11], v[44:47], v[202:205], v[8:11]
	v_mfma_f32_16x16x32_bf16 v[20:23], v[154:157], v[190:193], v[20:23]
	v_mfma_f32_16x16x32_bf16 v[16:19], v[162:165], v[190:193], v[16:19]
	v_mfma_f32_16x16x32_bf16 v[4:7], v[154:157], v[198:201], v[4:7]
	v_mfma_f32_16x16x32_bf16 v[0:3], v[162:165], v[198:201], v[0:3]
	v_mfma_f32_16x16x32_bf16 v[28:31], v[154:157], v[170:173], v[68:71]
	v_mfma_f32_16x16x32_bf16 v[36:39], v[162:165], v[170:173], v[64:67]
	v_mfma_f32_16x16x32_bf16 v[40:43], v[154:157], v[178:181], v[52:55]
	v_mfma_f32_16x16x32_bf16 v[44:47], v[162:165], v[178:181], v[48:51]
	v_mfma_f32_16x16x32_bf16 v[20:23], v[158:161], v[194:197], v[20:23]
	v_mfma_f32_16x16x32_bf16 v[16:19], v[166:169], v[194:197], v[16:19]
	v_mfma_f32_16x16x32_bf16 v[4:7], v[158:161], v[202:205], v[4:7]
	v_mfma_f32_16x16x32_bf16 v[0:3], v[166:169], v[202:205], v[0:3]
	v_mfma_f32_16x16x32_bf16 v[28:31], v[158:161], v[174:177], v[28:31]
	v_mfma_f32_16x16x32_bf16 v[36:39], v[166:169], v[174:177], v[36:39]
	v_mfma_f32_16x16x32_bf16 v[40:43], v[158:161], v[186:189], v[40:43]
	v_mfma_f32_16x16x32_bf16 v[44:47], v[166:169], v[186:189], v[44:47]
	s_barrier
; #define PG8_STAGE(bufoff, gbase, voff) do { _Pragma("unroll") for (int _i = 0; _i < 2; ++_i) \
;         __builtin_amdgcn_global_load_lds((const unsigned*)((const char*)(gbase) + (voff)[_i]), (LAS unsigned*)(lds + (bufoff) + ldsw + _i * 8192), 16, 0, 0); } while (0)
; #define PG8_LDA(dst, b, h) do { _Pragma("unroll") for (int m = 0; m < 4; ++m) _Pragma("unroll") for (int k = 0; k < 2; ++k) dst[m][k] = *(const LAS bf16x8*)(lds + PG8_SA(b, h) + aoff + m * 2048 + k * 1024); } while (0)
; #define PG8_LDB(dst, b, h) do { _Pragma("unroll") for (int n = 0; n < 2; ++n) _Pragma("unroll") for (int k = 0; k < 2; ++k) dst[n][k] = *(const LAS bf16x8*)(lds + PG8_SB(b, h) + boff + n * 2048 + k * 1024); } while (0)
; #define PG8_WAIT_V(n) asm volatile("s_waitcnt vmcnt(" #n ")" ::: "memory")
; #define PG8_WAIT_L(n) asm volatile("s_waitcnt lgkmcnt(" #n ")" ::: "memory")
; #define PG8_BAR __builtin_amdgcn_s_barrier()
; #define PG8_SCHED __builtin_amdgcn_sched_barrier(0)
; template <class Epi, class Sched>
; DI void gemm_phase(LAS unsigned char* lds, const Sched& S, const Epi& E) {
;     ...
;     for (int t = 0; t < nt; t += 2) {
;       const bool last = (t == nt - 2);
;       const char* a1 = cA + (size_t)(t + 1) * kstep;
;       const char* a2 = last ? nA : cA + (size_t)(t + 2) * kstep; const char* b2 = last ? nB : cB + (size_t)(t + 2) * kstep;
;       const char* a3 = a2 + kstep; const char* b3 = b2 + kstep;
;       PG8_LDB(B0, 0, 0); PG8_LDB(B1, 0, 1); PG8_SCHED; PG8_LDA(At, 0, 0); PG8_STAGE(PG8_SA(1, 1), a1 + hstep, voffA);
;       PG8_WAIT_V(8); PG8_WAIT_L(0); PG8_BAR; PG8_MMA(0, 0, At, B0); PG8_MMA(0, 1, At, B1); PG8_BAR; PG8_SCHED;
;       PG8_LDA(At, 0, 1); PG8_STAGE(PG8_SB(0, 0), b2, voffB); PG8_STAGE(PG8_SB(0, 1), b2 + hstep, voffB); PG8_STAGE(PG8_SA(0, 0), a2, voffA);
;       PG8_WAIT_V(8); PG8_WAIT_L(0); PG8_BAR; PG8_MMA(1, 0, At, B0); PG8_MMA(1, 1, At, B1); PG8_BAR; PG8_SCHED;
;       PG8_LDB(B0, 1, 0); PG8_LDB(B1, 1, 1); PG8_SCHED; PG8_LDA(At, 1, 0); PG8_STAGE(PG8_SA(0, 1), a2 + hstep, voffA);
;       PG8_WAIT_V(8); PG8_WAIT_L(0); PG8_BAR; PG8_MMA(0, 0, At, B0); PG8_MMA(0, 1, At, B1); PG8_BAR; PG8_SCHED;
;       PG8_LDA(At, 1, 1); PG8_STAGE(PG8_SB(1, 0), b3, voffB); PG8_STAGE(PG8_SB(1, 1), b3 + hstep, voffB); PG8_STAGE(PG8_SA(1, 0), a3, voffA);
;       PG8_WAIT_V(8); PG8_WAIT_L(0); PG8_BAR; PG8_MMA(1, 0, At, B0); PG8_MMA(1, 1, At, B1); PG8_BAR; PG8_SCHED;
;     }
	s_setprio 0
	s_add_i32 s58, 0, 0x18000
	s_add_i32 s59, 0, 0x1c000
	v_add_u32_e32 v68, s58, v183
	v_add_u32_e32 v166, s59, v183
	ds_read_b128 v[48:51], v68
	ds_read_b128 v[52:55], v68 offset:1024
	ds_read_b128 v[64:67], v68 offset:2048
	ds_read_b128 v[68:71], v68 offset:3072
	ds_read_b128 v[154:157], v166
	ds_read_b128 v[158:161], v166 offset:1024
	ds_read_b128 v[162:165], v166 offset:2048
	ds_read_b128 v[166:169], v166 offset:3072
	s_add_u32 s48, s48, 0x80000
	s_addc_u32 s49, s49, 0
	s_mov_b32 m0, s12
	ds_read_b128 v[170:173], v185 offset:32768
	ds_read_b128 v[174:177], v185 offset:33792
	ds_read_b128 v[178:181], v185 offset:34816
	ds_read_b128 v[186:189], v185 offset:35840
	ds_read_b128 v[190:193], v185 offset:36864
	ds_read_b128 v[194:197], v185 offset:37888
	ds_read_b128 v[198:201], v185 offset:38912
	ds_read_b128 v[202:205], v185 offset:39936
	global_load_lds_dwordx4 v144, s[48:49]
	s_mov_b32 m0, s18
	s_nop 0
	global_load_lds_dwordx4 v146, s[48:49]
	s_waitcnt vmcnt(8) lgkmcnt(0)
	s_setprio 1
	s_barrier
	v_mfma_f32_16x16x32_bf16 v[140:143], v[48:51], v[170:173], v[140:143]
	v_mfma_f32_16x16x32_bf16 v[136:139], v[64:67], v[170:173], v[136:139]
	v_mfma_f32_16x16x32_bf16 v[124:127], v[48:51], v[178:181], v[124:127]
	v_mfma_f32_16x16x32_bf16 v[120:123], v[64:67], v[178:181], v[120:123]
	v_mfma_f32_16x16x32_bf16 v[108:111], v[48:51], v[190:193], v[108:111]
	v_mfma_f32_16x16x32_bf16 v[104:107], v[64:67], v[190:193], v[104:107]
	v_mfma_f32_16x16x32_bf16 v[92:95], v[48:51], v[198:201], v[92:95]
	v_mfma_f32_16x16x32_bf16 v[88:91], v[64:67], v[198:201], v[88:91]
	v_mfma_f32_16x16x32_bf16 v[140:143], v[52:55], v[174:177], v[140:143]
	v_mfma_f32_16x16x32_bf16 v[136:139], v[68:71], v[174:177], v[136:139]
	v_mfma_f32_16x16x32_bf16 v[124:127], v[52:55], v[186:189], v[124:127]
	v_mfma_f32_16x16x32_bf16 v[120:123], v[68:71], v[186:189], v[120:123]
	v_mfma_f32_16x16x32_bf16 v[108:111], v[52:55], v[194:197], v[108:111]
	v_mfma_f32_16x16x32_bf16 v[104:107], v[68:71], v[194:197], v[104:107]
	v_mfma_f32_16x16x32_bf16 v[92:95], v[52:55], v[202:205], v[92:95]
	v_mfma_f32_16x16x32_bf16 v[88:91], v[68:71], v[202:205], v[88:91]
	v_mfma_f32_16x16x32_bf16 v[132:135], v[154:157], v[170:173], v[132:135]
	v_mfma_f32_16x16x32_bf16 v[128:131], v[162:165], v[170:173], v[128:131]
	v_mfma_f32_16x16x32_bf16 v[116:119], v[154:157], v[178:181], v[116:119]
	v_mfma_f32_16x16x32_bf16 v[112:115], v[162:165], v[178:181], v[112:115]
	v_mfma_f32_16x16x32_bf16 v[100:103], v[154:157], v[190:193], v[100:103]
	v_mfma_f32_16x16x32_bf16 v[96:99], v[162:165], v[190:193], v[96:99]
	v_mfma_f32_16x16x32_bf16 v[84:87], v[154:157], v[198:201], v[84:87]
	v_mfma_f32_16x16x32_bf16 v[80:83], v[162:165], v[198:201], v[80:83]
	v_mfma_f32_16x16x32_bf16 v[132:135], v[158:161], v[174:177], v[132:135]
	v_mfma_f32_16x16x32_bf16 v[128:131], v[166:169], v[174:177], v[128:131]
	v_mfma_f32_16x16x32_bf16 v[116:119], v[158:161], v[186:189], v[116:119]
	v_mfma_f32_16x16x32_bf16 v[112:115], v[166:169], v[186:189], v[112:115]
	v_mfma_f32_16x16x32_bf16 v[100:103], v[158:161], v[194:197], v[100:103]
	v_mfma_f32_16x16x32_bf16 v[96:99], v[166:169], v[194:197], v[96:99]
	v_mfma_f32_16x16x32_bf16 v[84:87], v[158:161], v[202:205], v[84:87]
	v_mfma_f32_16x16x32_bf16 v[80:83], v[166:169], v[202:205], v[80:83]
	s_barrier
	s_setprio 0
	s_add_i32 s48, s58, s9
	s_mov_b32 m0, s48
	ds_read_b128 v[170:173], v185 offset:49152
	ds_read_b128 v[174:177], v185 offset:50176
	ds_read_b128 v[178:181], v185 offset:51200
	ds_read_b128 v[186:189], v185 offset:52224
	ds_read_b128 v[190:193], v185 offset:53248
	ds_read_b128 v[194:197], v185 offset:54272
	ds_read_b128 v[198:201], v185 offset:55296
	ds_read_b128 v[202:205], v185 offset:56320
	global_load_lds_dwordx4 v208, s[72:73]
	s_add_i32 m0, s48, 0x2000
	s_add_u32 s26, s26, 0x80080
	s_addc_u32 s27, s27, 0
	s_add_i32 s48, s59, s9
	global_load_lds_dwordx4 v148, s[72:73]
	s_mov_b32 m0, s48
	s_nop 0
	global_load_lds_dwordx4 v208, s[26:27]
	s_add_i32 m0, s48, 0x2000
	s_nop 0
	global_load_lds_dwordx4 v148, s[26:27]
	s_mov_b32 m0, s51
	s_nop 0
	global_load_lds_dwordx4 v144, s[74:75]
	s_mov_b32 m0, s52
	s_nop 0
	global_load_lds_dwordx4 v146, s[74:75]
	s_waitcnt vmcnt(8) lgkmcnt(0)
	s_setprio 1
	s_barrier
	v_mfma_f32_16x16x32_bf16 v[76:79], v[48:51], v[170:173], v[76:79]
	v_mfma_f32_16x16x32_bf16 v[72:75], v[64:67], v[170:173], v[72:75]
	v_mfma_f32_16x16x32_bf16 v[60:63], v[48:51], v[178:181], v[60:63]
	v_mfma_f32_16x16x32_bf16 v[56:59], v[64:67], v[178:181], v[56:59]
	v_mfma_f32_16x16x32_bf16 v[32:35], v[48:51], v[190:193], v[32:35]
	v_mfma_f32_16x16x32_bf16 v[24:27], v[64:67], v[190:193], v[24:27]
	v_mfma_f32_16x16x32_bf16 v[12:15], v[48:51], v[198:201], v[12:15]
	v_mfma_f32_16x16x32_bf16 v[8:11], v[64:67], v[198:201], v[8:11]
	v_mfma_f32_16x16x32_bf16 v[76:79], v[52:55], v[174:177], v[76:79]
	v_mfma_f32_16x16x32_bf16 v[72:75], v[68:71], v[174:177], v[72:75]
	v_mfma_f32_16x16x32_bf16 v[60:63], v[52:55], v[186:189], v[60:63]
	v_mfma_f32_16x16x32_bf16 v[56:59], v[68:71], v[186:189], v[56:59]
	v_mfma_f32_16x16x32_bf16 v[32:35], v[52:55], v[194:197], v[32:35]
	v_mfma_f32_16x16x32_bf16 v[24:27], v[68:71], v[194:197], v[24:27]
	v_mfma_f32_16x16x32_bf16 v[12:15], v[52:55], v[202:205], v[12:15]
	v_mfma_f32_16x16x32_bf16 v[8:11], v[68:71], v[202:205], v[8:11]
	v_mfma_f32_16x16x32_bf16 v[28:31], v[154:157], v[170:173], v[28:31]
	v_mfma_f32_16x16x32_bf16 v[68:71], v[158:161], v[174:177], v[28:31]
	v_mfma_f32_16x16x32_bf16 v[28:31], v[162:165], v[170:173], v[36:39]
	v_mfma_f32_16x16x32_bf16 v[64:67], v[166:169], v[174:177], v[28:31]
	v_mfma_f32_16x16x32_bf16 v[28:31], v[154:157], v[178:181], v[40:43]
	v_mfma_f32_16x16x32_bf16 v[52:55], v[158:161], v[186:189], v[28:31]
	v_mfma_f32_16x16x32_bf16 v[28:31], v[162:165], v[178:181], v[44:47]
	v_mfma_f32_16x16x32_bf16 v[20:23], v[154:157], v[190:193], v[20:23]
	v_mfma_f32_16x16x32_bf16 v[16:19], v[162:165], v[190:193], v[16:19]
	v_mfma_f32_16x16x32_bf16 v[4:7], v[154:157], v[198:201], v[4:7]
	v_mfma_f32_16x16x32_bf16 v[0:3], v[162:165], v[198:201], v[0:3]
	v_mfma_f32_16x16x32_bf16 v[48:51], v[166:169], v[186:189], v[28:31]
	v_mfma_f32_16x16x32_bf16 v[20:23], v[158:161], v[194:197], v[20:23]
	v_mfma_f32_16x16x32_bf16 v[16:19], v[166:169], v[194:197], v[16:19]
	v_mfma_f32_16x16x32_bf16 v[4:7], v[158:161], v[202:205], v[4:7]
	v_mfma_f32_16x16x32_bf16 v[0:3], v[166:169], v[202:205], v[0:3]
	s_barrier
	s_setprio 0
	s_add_i32 s57, s57, 2
	s_add_u32 s36, s36, 0x100
	s_addc_u32 s37, s37, 0
	s_add_u32 s55, s55, 0x100
	s_addc_u32 s56, s56, 0
	s_cmp_gt_u32 s57, 29
	s_cbranch_scc0 .LBB0_969
	s_and_b64 vcc, exec, s[30:31]
	s_cbranch_vccz .LBB0_972
	s_barrier
